# one static s_setprio 1 for waves 4-7 across P6 (scan + attention), reset to 0 at P7 entry
# speedup vs baseline: 1.0100x; 1.0100x over previous
.LBB0_1050:
	s_cmpk_lt_u32 s73, 0x100
	s_cbranch_scc1 .Lprio6_skip
	s_setprio 1

.LBB0_1222:
	s_setprio 0
	s_cmp_lt_i32 s90, 8
	s_cselect_b64 s[8:9], -1, 0
	s_and_b64 s[0:1], s[8:9], s[0:1]
	s_andn2_b64 vcc, exec, s[0:1]
	s_cbranch_vccnz .LBB0_1230
	s_cmpk_gt_i32 s96, 0x2fff
	s_cbranch_scc1 .LBB0_1230
	v_readlane_b32 s12, v237, 2
	s_waitcnt vmcnt(0)
	v_lshlrev_b32_e32 v1, 2, v168
	v_readlane_b32 s13, v237, 3
	v_readlane_b32 s18, v237, 8
	v_readlane_b32 s19, v237, 9
	v_readlane_b32 s20, v237, 10
	v_readlane_b32 s21, v237, 11
	v_lshlrev_b32_e32 v2, 4, v168
	v_mov_b32_e32 v3, 0
	s_mov_b64 s[10:11], s[18:19]
	s_mov_b64 s[12:13], s[20:21]
	v_or_b32_e32 v4, 0x400, v1
	v_lshl_add_u64 v[10:11], s[10:11], 0, v[2:3]
	v_lshl_add_u64 v[12:13], s[12:13], 0, v[2:3]
	v_lshlrev_b32_e32 v2, 2, v4
	v_or_b32_e32 v5, 0x500, v1
	v_lshl_add_u64 v[14:15], s[10:11], 0, v[2:3]
	v_lshl_add_u64 v[16:17], s[12:13], 0, v[2:3]
	v_lshlrev_b32_e32 v2, 2, v5
	v_or_b32_e32 v6, 0x600, v1
	v_lshl_add_u64 v[18:19], s[10:11], 0, v[2:3]
	v_lshl_add_u64 v[20:21], s[12:13], 0, v[2:3]
	v_lshlrev_b32_e32 v2, 2, v6
	v_or_b32_e32 v7, 0x700, v1
	v_lshl_add_u64 v[22:23], s[10:11], 0, v[2:3]
	v_lshl_add_u64 v[24:25], s[12:13], 0, v[2:3]
	v_lshlrev_b32_e32 v2, 2, v7
	s_ashr_i32 s97, s96, 31
	v_lshl_add_u64 v[26:27], s[10:11], 0, v[2:3]
	s_waitcnt lgkmcnt(3)
	v_lshl_add_u64 v[28:29], s[12:13], 0, v[2:3]
	s_lshl_b64 s[2:3], s[96:97], 7
	v_lshrrev_b32_e32 v2, 2, v168
	s_waitcnt lgkmcnt(2)
	v_and_or_b32 v30, v2, 12, s2
	v_lshrrev_b32_e32 v2, 4, v4
	v_and_b32_e32 v2, 0x4c, v2
	v_or_b32_e32 v38, s2, v2
	v_lshrrev_b32_e32 v2, 4, v5
	v_and_b32_e32 v2, 0x5c, v2
	v_or_b32_e32 v40, s2, v2
	v_lshrrev_b32_e32 v2, 4, v6
	v_and_b32_e32 v2, 0x6c, v2
	v_or_b32_e32 v42, s2, v2
	v_lshrrev_b32_e32 v2, 4, v7
	v_and_b32_e32 v2, 0x7c, v2
	s_waitcnt lgkmcnt(1)
	v_mov_b32_e32 v31, s3
	v_mov_b32_e32 v33, s3
	v_mov_b32_e32 v35, s3
	v_mov_b32_e32 v37, s3
	v_mov_b32_e32 v39, s3
	v_mov_b32_e32 v41, s3
	v_mov_b32_e32 v43, s3
	v_or_b32_e32 v44, s2, v2
	v_mov_b32_e32 v45, s3
	s_mul_hi_i32 s2, s96, 0x3000
	s_mul_i32 s3, s96, 0x3000
	v_lshlrev_b32_e32 v2, 3, v168
	v_or_b32_e32 v46, s3, v2
	v_mov_b32_e32 v47, s2
	s_lshl_b64 s[2:3], s[96:97], 12
	v_readlane_b32 s14, v237, 4
	v_readlane_b32 s15, v237, 5
	v_readlane_b32 s16, v237, 6
	v_readlane_b32 s17, v237, 7
	v_readlane_b32 s22, v237, 12
	v_readlane_b32 s23, v237, 13
	v_readlane_b32 s24, v237, 14
	v_readlane_b32 s25, v237, 15
	v_readlane_b32 s26, v237, 16
	v_readlane_b32 s27, v237, 17
	s_ashr_i32 s95, s94, 31
	v_or_b32_e32 v48, s2, v2
	v_mov_b32_e32 v49, s3
	s_lshl_b64 s[2:3], s[96:97], 11
	v_cmp_eq_u32_e64 s[0:1], 0, v168
	s_lshl_b64 s[10:11], s[96:97], 2
	s_lshl_b64 s[12:13], s[94:95], 2
	s_lshl_b64 s[14:15], s[94:95], 7
	s_waitcnt lgkmcnt(0)
	v_or_b32_e32 v32, 16, v30
	v_or_b32_e32 v34, 32, v30
	v_or_b32_e32 v36, 48, v30
	s_mul_hi_i32 s17, s94, 0x3000
	s_mul_i32 s16, s94, 0x3000
	s_lshl_b64 s[18:19], s[94:95], 12
	v_or_b32_e32 v50, s2, v1
	v_mov_b32_e32 v51, s3
	s_lshl_b64 s[20:21], s[94:95], 11
	s_mov_b32 s22, 0x1a400000
	s_mov_b32 s23, 0x1a580000
	s_mov_b32 s24, 0x23a02000
	v_mov_b32_e32 v1, 0x3a27c5ac
	s_mov_b32 s25, 0xf800000
	v_mov_b32_e32 v100, 0x260
	v_mov_b32_e32 v101, 0x84000
	s_mov_b32 s26, 0x42fe0000
	s_movk_i32 s27, 0xff81
	s_mov_b32 s28, 0x40c0c00
	s_mov_b32 s29, 0x5c700000
	v_mov_b32_e32 v102, 0xa0000
	s_mov_b32 s30, 0x57300000
	v_mov_b32_e32 v103, 0x7f
	s_mov_b32 s31, s96
	s_branch .LBB0_1226
